# v2 plus: nt loads in conv (b gate, c*u rows)
# baseline (speedup 1.0000x reference)
.LBB0_158:
	s_or_b64 exec, exec, s[0:1]
	s_mov_b64 s[0:1], s[82:83]
	v_mov_b32_e32 v34, v0
	s_mov_b32 s2, s73
	s_mov_b32 s7, s72
	s_barrier
	s_load_dwordx2 s[2:3], s[0:1], 0x18
	v_lshlrev_b32_e32 v2, 3, v34
	v_and_b32_e32 v35, 0x3f8, v2
	v_mov_b32_e32 v149, 0
	v_lshlrev_b32_e32 v148, 2, v35
	s_waitcnt lgkmcnt(0)
	v_lshl_add_u64 v[6:7], s[2:3], 0, v[148:149]
	global_load_dwordx4 v[2:5], v148, s[2:3] offset:16
	global_load_dwordx4 v[14:17], v148, s[2:3]
	s_movk_i32 s2, 0x1000
	v_add_co_u32_e32 v30, vcc, s2, v6
	s_mov_b64 s[4:5], 0x1000
	s_nop 0
	v_addc_co_u32_e32 v31, vcc, 0, v7, vcc
	v_lshl_add_u64 v[26:27], v[6:7], 0, s[4:5]
	s_mov_b64 s[4:5], 0x2000
	v_add_co_u32_e32 v32, vcc, 0x2000, v6
	v_lshl_add_u64 v[28:29], v[6:7], 0, s[4:5]
	s_nop 0
	v_addc_co_u32_e32 v33, vcc, 0, v7, vcc
	global_load_dwordx4 v[18:21], v[30:31], off nt
	global_load_dwordx4 v[22:25], v[32:33], off nt
	global_load_dwordx4 v[10:13], v[26:27], off offset:16 nt
	global_load_dwordx4 v[6:9], v[28:29], off offset:16 nt
	s_load_dwordx2 s[0:1], s[0:1], 0x90
	s_lshl_b32 s2, s7, 3
	s_and_b32 s2, s2, 56
	s_bfe_u32 s3, s7, 0x30003
	s_or_b32 s6, s2, s3
	s_waitcnt lgkmcnt(0)
	s_add_u32 s2, s0, 0xdc00000
	v_ashrrev_i32_e32 v26, 3, v34
	s_addc_u32 s3, s1, 0
	s_andn2_b32 s7, s7, 63
	v_and_b32_e32 v26, -16, v26
	v_add_u32_e32 v26, s7, v26
	v_lshl_add_u32 v30, s6, 8, v26
	v_and_b32_e32 v27, 0xff0, v30
	v_cmp_ne_u32_e32 vcc, 0, v27
	v_ashrrev_i32_e32 v31, 31, v30
	v_lshlrev_b32_e32 v148, 1, v35
	v_mov_b32_e32 v186, 0
	v_mov_b32_e32 v184, 0
	v_mov_b32_e32 v187, 0
	v_mov_b32_e32 v185, 0
	v_mov_b32_e32 v180, 0
	v_mov_b32_e32 v178, 0
	v_mov_b32_e32 v181, 0
	v_mov_b32_e32 v179, 0
	v_mov_b32_e32 v194, 0
	v_mov_b32_e32 v195, 0
	v_mov_b32_e32 v154, 0
	v_mov_b32_e32 v155, 0
	v_mov_b32_e32 v190, 0
	v_mov_b32_e32 v191, 0
	v_mov_b32_e32 v192, 0
	v_mov_b32_e32 v193, 0
	s_and_saveexec_b64 s[4:5], vcc
	s_cbranch_execz .LBB0_160
	v_lshlrev_b64 v[32:33], 11, v[30:31]
	v_mov_b32_e32 v29, 0
	v_mov_b32_e32 v28, v148
	v_lshl_add_u64 v[32:33], s[2:3], 0, v[32:33]
	v_lshl_add_u64 v[28:29], v[32:33], 0, v[28:29]
	global_load_dwordx4 v[32:35], v[28:29], off offset:-4096 nt
	global_load_dwordx4 v[36:39], v[28:29], off offset:-2048 nt
	s_waitcnt vmcnt(1)
	v_lshlrev_b32_e32 v154, 16, v32
	v_and_b32_e32 v194, 0xffff0000, v32
	v_lshlrev_b32_e32 v155, 16, v33
	v_and_b32_e32 v195, 0xffff0000, v33
	v_lshlrev_b32_e32 v192, 16, v34
	v_and_b32_e32 v190, 0xffff0000, v34
	v_lshlrev_b32_e32 v193, 16, v35
	v_and_b32_e32 v191, 0xffff0000, v35
	s_waitcnt vmcnt(0)
	v_lshlrev_b32_e32 v186, 16, v36
	v_and_b32_e32 v184, 0xffff0000, v36
	v_lshlrev_b32_e32 v187, 16, v37
	v_and_b32_e32 v185, 0xffff0000, v37
	v_lshlrev_b32_e32 v180, 16, v38
	v_and_b32_e32 v178, 0xffff0000, v38
	v_lshlrev_b32_e32 v181, 16, v39
	v_and_b32_e32 v179, 0xffff0000, v39
.LBB0_160:
	s_or_b64 exec, exec, s[4:5]
	s_mul_i32 s6, s6, 0x160000
	s_add_u32 s4, s0, s6
	s_addc_u32 s5, s1, 0
	v_lshlrev_b32_e32 v26, 11, v26
	v_lshl_add_u64 v[28:29], s[4:5], 0, v[148:149]
	v_and_b32_e32 v26, 0x78000, v26
	v_mov_b32_e32 v27, v149
	v_lshl_add_u64 v[32:33], s[2:3], 0, v[148:149]
	v_lshl_add_u64 v[26:27], v[28:29], 0, v[26:27]
	s_mov_b64 s[2:3], 0x5000000
	v_lshl_add_u64 v[28:29], v[26:27], 0, s[2:3]
	s_mov_b32 s2, 0x5001000
	v_lshlrev_b64 v[196:197], 11, v[30:31]
	v_add_co_u32_e32 v34, vcc, s2, v26
	v_lshl_add_u64 v[36:37], v[32:33], 0, v[196:197]
	s_nop 0
	v_addc_co_u32_e32 v35, vcc, 0, v27, vcc
	global_load_dwordx4 v[198:201], v[36:37], off nt
	global_load_dwordx4 v[138:141], v[28:29], off offset:2048 nt
	global_load_dwordx4 v[202:205], v[34:35], off offset:-4096 nt
	global_load_dwordx4 v[130:133], v[34:35], off nt
	v_or_b32_e32 v28, 1, v30
	v_ashrrev_i32_e32 v29, 31, v28
	v_or_b32_e32 v36, 2, v30
	v_lshlrev_b64 v[188:189], 11, v[28:29]
	v_ashrrev_i32_e32 v37, 31, v36
	v_lshl_add_u64 v[28:29], v[32:33], 0, v[188:189]
	v_lshlrev_b64 v[182:183], 11, v[36:37]
	v_lshl_add_u64 v[36:37], v[32:33], 0, v[182:183]
	global_load_dwordx4 v[142:145], v[28:29], off nt
	global_load_dwordx4 v[134:137], v[36:37], off nt
	s_mov_b32 s2, 0x5002000
	v_or_b32_e32 v28, 3, v30
	v_add_co_u32_e32 v36, vcc, s2, v26
	v_ashrrev_i32_e32 v29, 31, v28
	s_nop 0
	v_addc_co_u32_e32 v37, vcc, 0, v27, vcc
	s_mov_b32 s2, 0x5003000
	v_lshlrev_b64 v[176:177], 11, v[28:29]
	v_add_co_u32_e32 v38, vcc, s2, v26
	v_lshl_add_u64 v[28:29], v[32:33], 0, v[176:177]
	s_nop 0
	v_addc_co_u32_e32 v39, vcc, 0, v27, vcc
	global_load_dwordx4 v[122:125], v[34:35], off offset:2048 nt
	global_load_dwordx4 v[114:117], v[38:39], off offset:-4096 nt
	global_load_dwordx4 v[126:129], v[28:29], off nt
	global_load_dwordx4 v[106:109], v[36:37], off offset:2048 nt
	v_or_b32_e32 v34, 4, v30
	v_ashrrev_i32_e32 v35, 31, v34
	v_or_b32_e32 v28, 5, v30
	v_lshlrev_b64 v[174:175], 11, v[34:35]
	v_ashrrev_i32_e32 v29, 31, v28
	v_lshl_add_u64 v[34:35], v[32:33], 0, v[174:175]
	v_lshlrev_b64 v[172:173], 11, v[28:29]
	v_lshl_add_u64 v[28:29], v[32:33], 0, v[172:173]
	global_load_dwordx4 v[118:121], v[34:35], off nt
	global_load_dwordx4 v[110:113], v[28:29], off nt
	v_or_b32_e32 v28, 6, v30
	v_ashrrev_i32_e32 v29, 31, v28
	v_or_b32_e32 v34, 7, v30
	v_or_b32_e32 v36, 8, v30
	v_lshlrev_b64 v[170:171], 11, v[28:29]
	v_ashrrev_i32_e32 v35, 31, v34
	v_ashrrev_i32_e32 v37, 31, v36
	v_lshl_add_u64 v[28:29], v[32:33], 0, v[170:171]
	v_lshlrev_b64 v[168:169], 11, v[34:35]
	s_mov_b32 s2, 0x5004000
	v_lshlrev_b64 v[166:167], 11, v[36:37]
	global_load_dwordx4 v[98:101], v[38:39], off nt
	global_load_dwordx4 v[90:93], v[38:39], off offset:2048 nt
	v_lshl_add_u64 v[34:35], v[32:33], 0, v[168:169]
	global_load_dwordx4 v[102:105], v[28:29], off nt
	global_load_dwordx4 v[94:97], v[34:35], off nt
	v_add_co_u32_e32 v28, vcc, s2, v26
	v_lshl_add_u64 v[36:37], v[32:33], 0, v[166:167]
	s_nop 0
	v_addc_co_u32_e32 v29, vcc, 0, v27, vcc
	global_load_dwordx4 v[82:85], v[36:37], off nt
	global_load_dwordx4 v[74:77], v[28:29], off offset:2048 nt
	v_or_b32_e32 v28, 9, v30
	s_mov_b32 s2, 0x5005000
	v_ashrrev_i32_e32 v29, 31, v28
	v_or_b32_e32 v36, 10, v30
	v_add_co_u32_e32 v34, vcc, s2, v26
	v_lshlrev_b64 v[164:165], 11, v[28:29]
	v_ashrrev_i32_e32 v37, 31, v36
	s_waitcnt vmcnt(22)
	v_mov_b32_e32 v150, v14
	v_mov_b32_e32 v151, v16
	v_mov_b32_e32 v16, v15
	v_mov_b32_e32 v14, v2
	v_mov_b32_e32 v15, v4
	v_mov_b32_e32 v4, v3
	s_waitcnt vmcnt(21)
	v_mov_b32_e32 v2, v18
	v_mov_b32_e32 v3, v20
	v_mov_b32_e32 v20, v19
	v_addc_co_u32_e32 v35, vcc, 0, v27, vcc
	v_lshl_add_u64 v[28:29], v[32:33], 0, v[164:165]
	v_lshlrev_b64 v[162:163], 11, v[36:37]
	v_pk_mul_f32 v[210:211], v[2:3], v[186:187]
	v_pk_mul_f32 v[18:19], v[20:21], v[184:185]
	global_load_dwordx4 v[86:89], v[34:35], off offset:-4096 nt
	global_load_dwordx4 v[66:69], v[34:35], off nt
	v_lshl_add_u64 v[36:37], v[32:33], 0, v[162:163]
	global_load_dwordx4 v[78:81], v[28:29], off nt
	global_load_dwordx4 v[70:73], v[36:37], off nt
	v_or_b32_e32 v28, 11, v30
	s_mov_b32 s2, 0x5006000
	s_waitcnt vmcnt(21)
	v_lshlrev_b32_e32 v209, 16, v199
	v_lshlrev_b32_e32 v208, 16, v198
	v_and_b32_e32 v199, 0xffff0000, v199
	v_and_b32_e32 v198, 0xffff0000, v198
	v_pk_fma_f32 v[210:211], v[150:151], v[154:155], v[210:211]
	v_mov_b32_e32 v155, v24
	v_pk_fma_f32 v[18:19], v[16:17], v[194:195], v[18:19]
	v_mov_b32_e32 v24, v23
	v_ashrrev_i32_e32 v29, 31, v28
	v_add_co_u32_e32 v36, vcc, s2, v26
	s_waitcnt vmcnt(19)
	v_lshlrev_b32_e32 v207, 16, v203
	v_lshlrev_b32_e32 v206, 16, v202
	v_and_b32_e32 v203, 0xffff0000, v203
	v_and_b32_e32 v202, 0xffff0000, v202
	v_pk_fma_f32 v[18:19], v[24:25], v[198:199], v[18:19]
	v_lshlrev_b64 v[160:161], 11, v[28:29]
	v_addc_co_u32_e32 v37, vcc, 0, v27, vcc
	s_mov_b32 s2, 0x5007000
	v_mov_b32_e32 v154, v22
	v_pk_mul_f32 v[194:195], v[18:19], v[202:203]
	v_mov_b32_e32 v18, v10
	v_mov_b32_e32 v19, v12
	v_mov_b32_e32 v12, v11
	v_lshl_add_u64 v[28:29], v[32:33], 0, v[160:161]
	v_add_co_u32_e32 v26, vcc, s2, v26
	v_pk_fma_f32 v[210:211], v[154:155], v[208:209], v[210:211]
	v_pk_mul_f32 v[22:23], v[18:19], v[180:181]
	v_pk_mul_f32 v[10:11], v[12:13], v[178:179]
	v_addc_co_u32_e32 v27, vcc, 0, v27, vcc
	global_load_dwordx4 v[58:61], v[34:35], off offset:2048 nt
	global_load_dwordx4 v[50:53], v[26:27], off offset:-4096 nt
	v_or_b32_e32 v34, 12, v30
	global_load_dwordx4 v[62:65], v[28:29], off nt
	global_load_dwordx4 v[42:45], v[36:37], off offset:2048 nt
	v_or_b32_e32 v28, 13, v30
	v_pk_mul_f32 v[206:207], v[210:211], v[206:207]
	v_lshlrev_b32_e32 v211, 16, v201
	v_lshlrev_b32_e32 v210, 16, v200
	v_and_b32_e32 v201, 0xffff0000, v201
	v_and_b32_e32 v200, 0xffff0000, v200
	v_pk_fma_f32 v[192:193], v[14:15], v[192:193], v[22:23]
	v_mov_b32_e32 v23, v8
	v_pk_fma_f32 v[10:11], v[4:5], v[190:191], v[10:11]
	v_mov_b32_e32 v8, v7
	v_ashrrev_i32_e32 v35, 31, v34
	v_ashrrev_i32_e32 v29, 31, v28
	v_lshlrev_b32_e32 v203, 16, v205
	v_lshlrev_b32_e32 v202, 16, v204
	v_and_b32_e32 v205, 0xffff0000, v205
	v_and_b32_e32 v204, 0xffff0000, v204
	v_mov_b32_e32 v22, v6
	v_pk_fma_f32 v[6:7], v[8:9], v[200:201], v[10:11]
	v_lshlrev_b64 v[158:159], 11, v[34:35]
	v_lshlrev_b64 v[156:157], 11, v[28:29]
	v_lshl_add_u64 v[148:149], s[0:1], 0, v[148:149]
	s_mov_b64 s[0:1], 0xa800000
	v_pk_fma_f32 v[192:193], v[22:23], v[210:211], v[192:193]
	v_pk_mul_f32 v[6:7], v[6:7], v[204:205]
	v_lshl_add_u64 v[34:35], v[32:33], 0, v[158:159]
	v_lshl_add_u64 v[28:29], v[32:33], 0, v[156:157]
	v_lshl_add_u64 v[148:149], v[148:149], 0, s[0:1]
	v_pk_mul_f32 v[192:193], v[192:193], v[202:203]
	v_bfe_u32 v10, v7, 16, 1
	v_bfe_u32 v11, v6, 16, 1
	v_bfe_u32 v190, v195, 16, 1
	v_bfe_u32 v191, v194, 16, 1
	s_movk_i32 s1, 0x7fff
	global_load_dwordx4 v[54:57], v[34:35], off nt
	global_load_dwordx4 v[46:49], v[28:29], off nt
	v_or_b32_e32 v28, 14, v30
	v_or_b32_e32 v30, 15, v30
	v_add3_u32 v194, v194, v191, s1
	v_add3_u32 v190, v195, v190, s1
	v_add3_u32 v6, v6, v11, s1
	v_add3_u32 v7, v7, v10, s1
	v_bfe_u32 v10, v206, 16, 1
	v_bfe_u32 v11, v207, 16, 1
	v_bfe_u32 v191, v192, 16, 1
	v_bfe_u32 v195, v193, 16, 1
	v_ashrrev_i32_e32 v29, 31, v28
	v_ashrrev_i32_e32 v31, 31, v30
	v_add3_u32 v193, v193, v195, s1
	v_add3_u32 v191, v192, v191, s1
	v_add3_u32 v11, v207, v11, s1
	v_add3_u32 v10, v206, v10, s1
	v_lshlrev_b64 v[152:153], 11, v[28:29]
	v_lshlrev_b64 v[146:147], 11, v[30:31]
	s_mov_b32 s0, 0xffff0000
	v_lshrrev_b32_e32 v10, 16, v10
	v_lshrrev_b32_e32 v11, 16, v11
	v_lshrrev_b32_e32 v191, 16, v191
	v_lshrrev_b32_e32 v192, 16, v193
	v_lshl_add_u64 v[38:39], v[32:33], 0, v[152:153]
	v_lshl_add_u64 v[30:31], v[32:33], 0, v[146:147]
	v_and_or_b32 v193, v7, s0, v192
	v_and_or_b32 v192, v6, s0, v191
	v_and_or_b32 v191, v190, s0, v11
	v_and_or_b32 v190, v194, s0, v10
	v_lshl_add_u64 v[6:7], v[148:149], 0, v[196:197]
	global_load_dwordx4 v[34:37], v[26:27], off nt
	s_nop 0
	global_load_dwordx4 v[26:29], v[26:27], off offset:2048 nt
	s_nop 0
	global_load_dwordx4 v[38:41], v[38:39], off nt
	s_nop 0
	global_load_dwordx4 v[30:33], v[30:31], off nt
	v_and_b32_e32 v11, 0xffff0000, v139
	global_store_dwordx4 v[6:7], v[190:193], off
	v_lshlrev_b32_e32 v7, 16, v139
	v_lshlrev_b32_e32 v6, 16, v138
	v_and_b32_e32 v10, 0xffff0000, v138
	v_pk_mul_f32 v[138:139], v[2:3], v[208:209]
	s_waitcnt vmcnt(28)
	v_lshlrev_b32_e32 v191, 16, v143
	v_lshlrev_b32_e32 v190, 16, v142
	v_pk_fma_f32 v[138:139], v[150:151], v[186:187], v[138:139]
	v_and_b32_e32 v143, 0xffff0000, v143
	v_pk_fma_f32 v[138:139], v[154:155], v[190:191], v[138:139]
	v_and_b32_e32 v142, 0xffff0000, v142
	v_pk_mul_f32 v[6:7], v[138:139], v[6:7]
	v_pk_mul_f32 v[138:139], v[20:21], v[198:199]
	v_pk_mul_f32 v[186:187], v[18:19], v[210:211]
	v_pk_fma_f32 v[138:139], v[16:17], v[184:185], v[138:139]
	v_lshlrev_b32_e32 v185, 16, v145
	v_pk_fma_f32 v[138:139], v[24:25], v[142:143], v[138:139]
	v_lshlrev_b32_e32 v184, 16, v144
	v_pk_fma_f32 v[180:181], v[14:15], v[180:181], v[186:187]
	v_pk_mul_f32 v[10:11], v[138:139], v[10:11]
	v_lshlrev_b32_e32 v139, 16, v141
	v_lshlrev_b32_e32 v138, 16, v140
	v_pk_fma_f32 v[180:181], v[22:23], v[184:185], v[180:181]
	v_and_b32_e32 v145, 0xffff0000, v145
	v_pk_mul_f32 v[138:139], v[180:181], v[138:139]
	v_pk_mul_f32 v[180:181], v[12:13], v[200:201]
	v_and_b32_e32 v144, 0xffff0000, v144
	v_pk_fma_f32 v[178:179], v[4:5], v[178:179], v[180:181]
	v_and_b32_e32 v141, 0xffff0000, v141
	v_and_b32_e32 v140, 0xffff0000, v140
	v_pk_fma_f32 v[178:179], v[8:9], v[144:145], v[178:179]
	v_bfe_u32 v180, v11, 16, 1
	v_pk_mul_f32 v[140:141], v[178:179], v[140:141]
	v_bfe_u32 v181, v10, 16, 1
	v_bfe_u32 v178, v141, 16, 1
	v_bfe_u32 v179, v140, 16, 1
	v_add3_u32 v10, v10, v181, s1
	v_add3_u32 v11, v11, v180, s1
	v_add3_u32 v140, v140, v179, s1
	v_add3_u32 v141, v141, v178, s1
	v_bfe_u32 v178, v6, 16, 1
	v_bfe_u32 v179, v7, 16, 1
	v_bfe_u32 v180, v138, 16, 1
	v_bfe_u32 v181, v139, 16, 1
	v_add3_u32 v139, v139, v181, s1
	v_add3_u32 v138, v138, v180, s1
	v_add3_u32 v7, v7, v179, s1
	v_add3_u32 v6, v6, v178, s1
	v_lshrrev_b32_e32 v6, 16, v6
	v_lshrrev_b32_e32 v7, 16, v7
	v_lshrrev_b32_e32 v138, 16, v138
	v_lshrrev_b32_e32 v139, 16, v139
	v_and_or_b32 v141, v141, s0, v139
	v_and_or_b32 v140, v140, s0, v138
	v_and_or_b32 v139, v11, s0, v7
	v_and_or_b32 v138, v10, s0, v6
	v_lshl_add_u64 v[6:7], v[148:149], 0, v[188:189]
	global_store_dwordx4 v[6:7], v[138:141], off
	v_lshlrev_b32_e32 v7, 16, v131
	v_lshlrev_b32_e32 v6, 16, v130
	v_and_b32_e32 v11, 0xffff0000, v131
	v_and_b32_e32 v10, 0xffff0000, v130
	v_pk_mul_f32 v[130:131], v[2:3], v[190:191]
	s_waitcnt vmcnt(28)
	v_lshlrev_b32_e32 v139, 16, v135
	v_lshlrev_b32_e32 v138, 16, v134
	v_pk_fma_f32 v[130:131], v[150:151], v[208:209], v[130:131]
	v_and_b32_e32 v135, 0xffff0000, v135
	v_pk_fma_f32 v[130:131], v[154:155], v[138:139], v[130:131]
	v_and_b32_e32 v134, 0xffff0000, v134
	v_pk_mul_f32 v[6:7], v[130:131], v[6:7]
	v_pk_mul_f32 v[130:131], v[20:21], v[142:143]
	v_pk_mul_f32 v[178:179], v[18:19], v[184:185]
	v_pk_fma_f32 v[130:131], v[16:17], v[198:199], v[130:131]
	v_lshlrev_b32_e32 v141, 16, v137
	v_pk_fma_f32 v[130:131], v[24:25], v[134:135], v[130:131]
	v_lshlrev_b32_e32 v140, 16, v136
	v_pk_fma_f32 v[178:179], v[14:15], v[210:211], v[178:179]
	v_pk_mul_f32 v[10:11], v[130:131], v[10:11]
	v_lshlrev_b32_e32 v131, 16, v133
	v_lshlrev_b32_e32 v130, 16, v132
	v_pk_fma_f32 v[178:179], v[22:23], v[140:141], v[178:179]
	v_and_b32_e32 v137, 0xffff0000, v137
	v_pk_mul_f32 v[130:131], v[178:179], v[130:131]
	v_pk_mul_f32 v[178:179], v[12:13], v[144:145]
	v_and_b32_e32 v136, 0xffff0000, v136
	v_pk_fma_f32 v[178:179], v[4:5], v[200:201], v[178:179]
	v_and_b32_e32 v133, 0xffff0000, v133
	v_and_b32_e32 v132, 0xffff0000, v132
	v_pk_fma_f32 v[178:179], v[8:9], v[136:137], v[178:179]
	v_bfe_u32 v180, v11, 16, 1
	v_pk_mul_f32 v[132:133], v[178:179], v[132:133]
	v_bfe_u32 v181, v10, 16, 1
	v_bfe_u32 v178, v133, 16, 1
	v_bfe_u32 v179, v132, 16, 1
	v_add3_u32 v10, v10, v181, s1
	v_add3_u32 v11, v11, v180, s1
	v_add3_u32 v132, v132, v179, s1
	v_add3_u32 v133, v133, v178, s1
	v_bfe_u32 v178, v6, 16, 1
	v_bfe_u32 v179, v7, 16, 1
	v_bfe_u32 v180, v130, 16, 1
	v_bfe_u32 v181, v131, 16, 1
	v_add3_u32 v131, v131, v181, s1
	v_add3_u32 v130, v130, v180, s1
	v_add3_u32 v7, v7, v179, s1
	v_add3_u32 v6, v6, v178, s1
	v_lshrrev_b32_e32 v6, 16, v6
	v_lshrrev_b32_e32 v7, 16, v7
	v_lshrrev_b32_e32 v130, 16, v130
	v_lshrrev_b32_e32 v131, 16, v131
	v_and_or_b32 v133, v133, s0, v131
	v_and_or_b32 v132, v132, s0, v130
	v_and_or_b32 v131, v11, s0, v7
	v_and_or_b32 v130, v10, s0, v6
	v_lshl_add_u64 v[6:7], v[148:149], 0, v[182:183]
	global_store_dwordx4 v[6:7], v[130:133], off
	s_waitcnt vmcnt(28)
	v_lshlrev_b32_e32 v7, 16, v123
	v_lshlrev_b32_e32 v6, 16, v122
	v_and_b32_e32 v11, 0xffff0000, v123
	v_and_b32_e32 v10, 0xffff0000, v122
	v_pk_mul_f32 v[122:123], v[2:3], v[138:139]
	s_waitcnt vmcnt(26)
	v_lshlrev_b32_e32 v131, 16, v127
	v_lshlrev_b32_e32 v130, 16, v126
	v_pk_fma_f32 v[122:123], v[150:151], v[190:191], v[122:123]
	v_and_b32_e32 v127, 0xffff0000, v127
	v_pk_fma_f32 v[122:123], v[154:155], v[130:131], v[122:123]
	v_and_b32_e32 v126, 0xffff0000, v126
	v_pk_mul_f32 v[6:7], v[122:123], v[6:7]
	v_pk_mul_f32 v[122:123], v[20:21], v[134:135]
	v_lshlrev_b32_e32 v133, 16, v129
	v_pk_fma_f32 v[122:123], v[16:17], v[142:143], v[122:123]
	v_pk_mul_f32 v[142:143], v[18:19], v[140:141]
	v_pk_fma_f32 v[122:123], v[24:25], v[126:127], v[122:123]
	v_lshlrev_b32_e32 v132, 16, v128
	v_pk_fma_f32 v[142:143], v[14:15], v[184:185], v[142:143]
	v_pk_mul_f32 v[10:11], v[122:123], v[10:11]
	v_lshlrev_b32_e32 v123, 16, v125
	v_lshlrev_b32_e32 v122, 16, v124
	v_pk_fma_f32 v[142:143], v[22:23], v[132:133], v[142:143]
	v_and_b32_e32 v129, 0xffff0000, v129
	v_pk_mul_f32 v[122:123], v[142:143], v[122:123]
	v_pk_mul_f32 v[142:143], v[12:13], v[136:137]
	v_and_b32_e32 v128, 0xffff0000, v128
	v_pk_fma_f32 v[142:143], v[4:5], v[144:145], v[142:143]
	v_and_b32_e32 v125, 0xffff0000, v125
	v_and_b32_e32 v124, 0xffff0000, v124
	v_pk_fma_f32 v[142:143], v[8:9], v[128:129], v[142:143]
	v_bfe_u32 v144, v11, 16, 1
	v_pk_mul_f32 v[124:125], v[142:143], v[124:125]
	v_bfe_u32 v145, v10, 16, 1
	v_bfe_u32 v142, v125, 16, 1
	v_bfe_u32 v143, v124, 16, 1
	v_add3_u32 v10, v10, v145, s1
	v_add3_u32 v11, v11, v144, s1
	v_add3_u32 v124, v124, v143, s1
	v_add3_u32 v125, v125, v142, s1
	v_bfe_u32 v142, v6, 16, 1
	v_bfe_u32 v143, v7, 16, 1
	v_bfe_u32 v144, v122, 16, 1
	v_bfe_u32 v145, v123, 16, 1
	v_add3_u32 v123, v123, v145, s1
	v_add3_u32 v122, v122, v144, s1
	v_add3_u32 v7, v7, v143, s1
	v_add3_u32 v6, v6, v142, s1
	v_lshrrev_b32_e32 v6, 16, v6
	v_lshrrev_b32_e32 v7, 16, v7
	v_lshrrev_b32_e32 v122, 16, v122
	v_lshrrev_b32_e32 v123, 16, v123
	v_and_or_b32 v125, v125, s0, v123
	v_and_or_b32 v124, v124, s0, v122
	v_and_or_b32 v123, v11, s0, v7
	v_and_or_b32 v122, v10, s0, v6
	v_lshl_add_u64 v[6:7], v[148:149], 0, v[176:177]
	global_store_dwordx4 v[6:7], v[122:125], off
	v_lshlrev_b32_e32 v7, 16, v115
	v_lshlrev_b32_e32 v6, 16, v114
	v_and_b32_e32 v11, 0xffff0000, v115
	v_and_b32_e32 v10, 0xffff0000, v114
	v_pk_mul_f32 v[114:115], v[2:3], v[130:131]
	s_waitcnt vmcnt(25)
	v_lshlrev_b32_e32 v123, 16, v119
	v_lshlrev_b32_e32 v122, 16, v118
	v_pk_fma_f32 v[114:115], v[150:151], v[138:139], v[114:115]
	v_and_b32_e32 v119, 0xffff0000, v119
	v_pk_fma_f32 v[114:115], v[154:155], v[122:123], v[114:115]
	v_and_b32_e32 v118, 0xffff0000, v118
	v_pk_mul_f32 v[6:7], v[114:115], v[6:7]
	v_pk_mul_f32 v[114:115], v[20:21], v[126:127]
	v_lshlrev_b32_e32 v125, 16, v121
	v_pk_fma_f32 v[114:115], v[16:17], v[134:135], v[114:115]
	v_pk_mul_f32 v[134:135], v[18:19], v[132:133]
	v_pk_fma_f32 v[114:115], v[24:25], v[118:119], v[114:115]
	v_lshlrev_b32_e32 v124, 16, v120
	v_pk_fma_f32 v[134:135], v[14:15], v[140:141], v[134:135]
	v_pk_mul_f32 v[10:11], v[114:115], v[10:11]
	v_lshlrev_b32_e32 v115, 16, v117
	v_lshlrev_b32_e32 v114, 16, v116
	v_pk_fma_f32 v[134:135], v[22:23], v[124:125], v[134:135]
	v_and_b32_e32 v121, 0xffff0000, v121
	v_pk_mul_f32 v[114:115], v[134:135], v[114:115]
	v_pk_mul_f32 v[134:135], v[12:13], v[128:129]
	v_and_b32_e32 v120, 0xffff0000, v120
	v_pk_fma_f32 v[134:135], v[4:5], v[136:137], v[134:135]
	v_and_b32_e32 v117, 0xffff0000, v117
	v_and_b32_e32 v116, 0xffff0000, v116
	v_pk_fma_f32 v[134:135], v[8:9], v[120:121], v[134:135]
	v_bfe_u32 v136, v11, 16, 1
	v_pk_mul_f32 v[116:117], v[134:135], v[116:117]
	v_bfe_u32 v137, v10, 16, 1
	v_bfe_u32 v134, v117, 16, 1
	v_bfe_u32 v135, v116, 16, 1
	v_add3_u32 v10, v10, v137, s1
	v_add3_u32 v11, v11, v136, s1
	v_add3_u32 v116, v116, v135, s1
	v_add3_u32 v117, v117, v134, s1
	v_bfe_u32 v134, v6, 16, 1
	v_bfe_u32 v135, v7, 16, 1
	v_bfe_u32 v136, v114, 16, 1
	v_bfe_u32 v137, v115, 16, 1
	v_add3_u32 v115, v115, v137, s1
	v_add3_u32 v114, v114, v136, s1
	v_add3_u32 v7, v7, v135, s1
	v_add3_u32 v6, v6, v134, s1
	v_lshrrev_b32_e32 v6, 16, v6
	v_lshrrev_b32_e32 v7, 16, v7
	v_lshrrev_b32_e32 v114, 16, v114
	v_lshrrev_b32_e32 v115, 16, v115
	v_and_or_b32 v117, v117, s0, v115
	v_and_or_b32 v116, v116, s0, v114
	v_and_or_b32 v115, v11, s0, v7
	v_and_or_b32 v114, v10, s0, v6
	v_lshl_add_u64 v[6:7], v[148:149], 0, v[174:175]
	global_store_dwordx4 v[6:7], v[114:117], off
	v_lshlrev_b32_e32 v7, 16, v107
	v_lshlrev_b32_e32 v6, 16, v106
	v_and_b32_e32 v11, 0xffff0000, v107
	v_and_b32_e32 v10, 0xffff0000, v106
	v_pk_mul_f32 v[106:107], v[2:3], v[122:123]
	s_waitcnt vmcnt(25)
	v_lshlrev_b32_e32 v115, 16, v111
	v_lshlrev_b32_e32 v114, 16, v110
	v_pk_fma_f32 v[106:107], v[150:151], v[130:131], v[106:107]
	v_and_b32_e32 v111, 0xffff0000, v111
	v_pk_fma_f32 v[106:107], v[154:155], v[114:115], v[106:107]
	v_and_b32_e32 v110, 0xffff0000, v110
	v_pk_mul_f32 v[6:7], v[106:107], v[6:7]
	v_pk_mul_f32 v[106:107], v[20:21], v[118:119]
	v_lshlrev_b32_e32 v117, 16, v113
	v_pk_fma_f32 v[106:107], v[16:17], v[126:127], v[106:107]
	v_pk_mul_f32 v[126:127], v[18:19], v[124:125]
	v_pk_fma_f32 v[106:107], v[24:25], v[110:111], v[106:107]
	v_lshlrev_b32_e32 v116, 16, v112
	v_pk_fma_f32 v[126:127], v[14:15], v[132:133], v[126:127]
	v_pk_mul_f32 v[10:11], v[106:107], v[10:11]
	v_lshlrev_b32_e32 v107, 16, v109
	v_lshlrev_b32_e32 v106, 16, v108
	v_pk_fma_f32 v[126:127], v[22:23], v[116:117], v[126:127]
	v_and_b32_e32 v113, 0xffff0000, v113
	v_pk_mul_f32 v[106:107], v[126:127], v[106:107]
	v_pk_mul_f32 v[126:127], v[12:13], v[120:121]
	v_and_b32_e32 v112, 0xffff0000, v112
	v_pk_fma_f32 v[126:127], v[4:5], v[128:129], v[126:127]
	v_and_b32_e32 v109, 0xffff0000, v109
	v_and_b32_e32 v108, 0xffff0000, v108
	v_pk_fma_f32 v[126:127], v[8:9], v[112:113], v[126:127]
	v_bfe_u32 v128, v11, 16, 1
	v_pk_mul_f32 v[108:109], v[126:127], v[108:109]
	v_bfe_u32 v129, v10, 16, 1
	v_bfe_u32 v126, v109, 16, 1
	v_bfe_u32 v127, v108, 16, 1
	v_add3_u32 v10, v10, v129, s1
	v_add3_u32 v11, v11, v128, s1
	v_add3_u32 v108, v108, v127, s1
	v_add3_u32 v109, v109, v126, s1
	v_bfe_u32 v126, v6, 16, 1
	v_bfe_u32 v127, v7, 16, 1
	v_bfe_u32 v128, v106, 16, 1
	v_bfe_u32 v129, v107, 16, 1
	v_add3_u32 v107, v107, v129, s1
	v_add3_u32 v106, v106, v128, s1
	v_add3_u32 v7, v7, v127, s1
	v_add3_u32 v6, v6, v126, s1
	v_lshrrev_b32_e32 v6, 16, v6
	v_lshrrev_b32_e32 v7, 16, v7
	v_lshrrev_b32_e32 v106, 16, v106
	v_lshrrev_b32_e32 v107, 16, v107
	v_and_or_b32 v109, v109, s0, v107
	v_and_or_b32 v108, v108, s0, v106
	v_and_or_b32 v107, v11, s0, v7
	v_and_or_b32 v106, v10, s0, v6
	v_lshl_add_u64 v[6:7], v[148:149], 0, v[172:173]
	global_store_dwordx4 v[6:7], v[106:109], off
	s_waitcnt vmcnt(25)
	v_lshlrev_b32_e32 v7, 16, v99
	v_lshlrev_b32_e32 v6, 16, v98
	v_and_b32_e32 v11, 0xffff0000, v99
	v_and_b32_e32 v10, 0xffff0000, v98
	v_pk_mul_f32 v[98:99], v[2:3], v[114:115]
	s_waitcnt vmcnt(23)
	v_lshlrev_b32_e32 v107, 16, v103
	v_lshlrev_b32_e32 v106, 16, v102
	v_pk_fma_f32 v[98:99], v[150:151], v[122:123], v[98:99]
	v_and_b32_e32 v103, 0xffff0000, v103
	v_pk_fma_f32 v[98:99], v[154:155], v[106:107], v[98:99]
	v_and_b32_e32 v102, 0xffff0000, v102
	v_pk_mul_f32 v[6:7], v[98:99], v[6:7]
	v_pk_mul_f32 v[98:99], v[20:21], v[110:111]
	v_lshlrev_b32_e32 v109, 16, v105
	v_pk_fma_f32 v[98:99], v[16:17], v[118:119], v[98:99]
	v_pk_mul_f32 v[118:119], v[18:19], v[116:117]
	v_pk_fma_f32 v[98:99], v[24:25], v[102:103], v[98:99]
	v_lshlrev_b32_e32 v108, 16, v104
	v_pk_fma_f32 v[118:119], v[14:15], v[124:125], v[118:119]
	v_pk_mul_f32 v[10:11], v[98:99], v[10:11]
	v_lshlrev_b32_e32 v99, 16, v101
	v_lshlrev_b32_e32 v98, 16, v100
	v_pk_fma_f32 v[118:119], v[22:23], v[108:109], v[118:119]
	v_and_b32_e32 v105, 0xffff0000, v105
	v_pk_mul_f32 v[98:99], v[118:119], v[98:99]
	v_pk_mul_f32 v[118:119], v[12:13], v[112:113]
	v_and_b32_e32 v104, 0xffff0000, v104
	v_pk_fma_f32 v[118:119], v[4:5], v[120:121], v[118:119]
	v_and_b32_e32 v101, 0xffff0000, v101
	v_and_b32_e32 v100, 0xffff0000, v100
	v_pk_fma_f32 v[118:119], v[8:9], v[104:105], v[118:119]
	v_bfe_u32 v120, v11, 16, 1
	v_pk_mul_f32 v[100:101], v[118:119], v[100:101]
	v_bfe_u32 v121, v10, 16, 1
	v_bfe_u32 v118, v101, 16, 1
	v_bfe_u32 v119, v100, 16, 1
	v_add3_u32 v10, v10, v121, s1
	v_add3_u32 v11, v11, v120, s1
	v_add3_u32 v100, v100, v119, s1
	v_add3_u32 v101, v101, v118, s1
	v_bfe_u32 v118, v6, 16, 1
	v_bfe_u32 v119, v7, 16, 1
	v_bfe_u32 v120, v98, 16, 1
	v_bfe_u32 v121, v99, 16, 1
	v_add3_u32 v99, v99, v121, s1
	v_add3_u32 v98, v98, v120, s1
	v_add3_u32 v7, v7, v119, s1
	v_add3_u32 v6, v6, v118, s1
	v_lshrrev_b32_e32 v6, 16, v6
	v_lshrrev_b32_e32 v7, 16, v7
	v_lshrrev_b32_e32 v98, 16, v98
	v_lshrrev_b32_e32 v99, 16, v99
	v_and_or_b32 v101, v101, s0, v99
	v_and_or_b32 v100, v100, s0, v98
	v_and_or_b32 v99, v11, s0, v7
	v_and_or_b32 v98, v10, s0, v6
	v_lshl_add_u64 v[6:7], v[148:149], 0, v[170:171]
	global_store_dwordx4 v[6:7], v[98:101], off
	v_lshlrev_b32_e32 v7, 16, v91
	v_lshlrev_b32_e32 v6, 16, v90
	v_and_b32_e32 v11, 0xffff0000, v91
	v_and_b32_e32 v10, 0xffff0000, v90
	v_pk_mul_f32 v[90:91], v[2:3], v[106:107]
	s_waitcnt vmcnt(23)
	v_lshlrev_b32_e32 v99, 16, v95
	v_lshlrev_b32_e32 v98, 16, v94
	v_pk_fma_f32 v[90:91], v[150:151], v[114:115], v[90:91]
	v_and_b32_e32 v95, 0xffff0000, v95
	v_pk_fma_f32 v[90:91], v[154:155], v[98:99], v[90:91]
	v_and_b32_e32 v94, 0xffff0000, v94
	v_pk_mul_f32 v[6:7], v[90:91], v[6:7]
	v_pk_mul_f32 v[90:91], v[20:21], v[102:103]
	v_lshlrev_b32_e32 v101, 16, v97
	v_pk_fma_f32 v[90:91], v[16:17], v[110:111], v[90:91]
	v_pk_mul_f32 v[110:111], v[18:19], v[108:109]
	v_pk_fma_f32 v[90:91], v[24:25], v[94:95], v[90:91]
	v_lshlrev_b32_e32 v100, 16, v96
	v_pk_fma_f32 v[110:111], v[14:15], v[116:117], v[110:111]
	v_pk_mul_f32 v[10:11], v[90:91], v[10:11]
	v_lshlrev_b32_e32 v91, 16, v93
	v_lshlrev_b32_e32 v90, 16, v92
	v_pk_fma_f32 v[110:111], v[22:23], v[100:101], v[110:111]
	v_and_b32_e32 v97, 0xffff0000, v97
	v_pk_mul_f32 v[90:91], v[110:111], v[90:91]
	v_pk_mul_f32 v[110:111], v[12:13], v[104:105]
	v_and_b32_e32 v96, 0xffff0000, v96
	v_pk_fma_f32 v[110:111], v[4:5], v[112:113], v[110:111]
	v_and_b32_e32 v93, 0xffff0000, v93
	v_and_b32_e32 v92, 0xffff0000, v92
	v_pk_fma_f32 v[110:111], v[8:9], v[96:97], v[110:111]
	v_bfe_u32 v112, v11, 16, 1
	v_pk_mul_f32 v[92:93], v[110:111], v[92:93]
	v_bfe_u32 v113, v10, 16, 1
	v_bfe_u32 v110, v93, 16, 1
	v_bfe_u32 v111, v92, 16, 1
	v_add3_u32 v10, v10, v113, s1
	v_add3_u32 v11, v11, v112, s1
	v_add3_u32 v92, v92, v111, s1
	v_add3_u32 v93, v93, v110, s1
	v_bfe_u32 v110, v6, 16, 1
	v_bfe_u32 v111, v7, 16, 1
	v_bfe_u32 v112, v90, 16, 1
	v_bfe_u32 v113, v91, 16, 1
	v_add3_u32 v91, v91, v113, s1
	v_add3_u32 v90, v90, v112, s1
	v_add3_u32 v7, v7, v111, s1
	v_add3_u32 v6, v6, v110, s1
	v_lshrrev_b32_e32 v6, 16, v6
	v_lshrrev_b32_e32 v7, 16, v7
	v_lshrrev_b32_e32 v90, 16, v90
	v_lshrrev_b32_e32 v91, 16, v91
	v_and_or_b32 v93, v93, s0, v91
	v_and_or_b32 v92, v92, s0, v90
	v_and_or_b32 v91, v11, s0, v7
	v_and_or_b32 v90, v10, s0, v6
	v_lshl_add_u64 v[6:7], v[148:149], 0, v[168:169]
	global_store_dwordx4 v[6:7], v[90:93], off
	s_waitcnt vmcnt(21)
	v_lshlrev_b32_e32 v7, 16, v87
	v_lshlrev_b32_e32 v6, 16, v86
	v_and_b32_e32 v11, 0xffff0000, v87
	v_and_b32_e32 v10, 0xffff0000, v86
	v_lshlrev_b32_e32 v87, 16, v83
	v_lshlrev_b32_e32 v86, 16, v82
	v_and_b32_e32 v91, 0xffff0000, v83
	v_and_b32_e32 v90, 0xffff0000, v82
	v_pk_mul_f32 v[82:83], v[2:3], v[98:99]
	v_lshlrev_b32_e32 v93, 16, v85
	v_pk_fma_f32 v[82:83], v[150:151], v[106:107], v[82:83]
	v_lshlrev_b32_e32 v92, 16, v84
	v_pk_fma_f32 v[82:83], v[154:155], v[86:87], v[82:83]
	s_mov_b32 s2, s73
	v_pk_mul_f32 v[6:7], v[82:83], v[6:7]
	v_pk_mul_f32 v[82:83], v[20:21], v[94:95]
	s_mov_b32 s12, s72
	v_pk_fma_f32 v[82:83], v[16:17], v[102:103], v[82:83]
	v_and_b32_e32 v103, 0xffff0000, v85
	v_and_b32_e32 v102, 0xffff0000, v84
	v_pk_mul_f32 v[84:85], v[18:19], v[100:101]
	v_pk_fma_f32 v[82:83], v[24:25], v[90:91], v[82:83]
	v_pk_fma_f32 v[84:85], v[14:15], v[108:109], v[84:85]
	v_pk_mul_f32 v[10:11], v[82:83], v[10:11]
	v_lshlrev_b32_e32 v83, 16, v89
	v_lshlrev_b32_e32 v82, 16, v88
	v_pk_fma_f32 v[84:85], v[22:23], v[92:93], v[84:85]
	v_and_b32_e32 v89, 0xffff0000, v89
	v_pk_mul_f32 v[82:83], v[84:85], v[82:83]
	v_pk_mul_f32 v[84:85], v[12:13], v[96:97]
	v_and_b32_e32 v88, 0xffff0000, v88
	v_pk_fma_f32 v[84:85], v[4:5], v[104:105], v[84:85]
	v_bfe_u32 v104, v11, 16, 1
	v_pk_fma_f32 v[84:85], v[8:9], v[102:103], v[84:85]
	v_bfe_u32 v105, v10, 16, 1
	v_pk_mul_f32 v[84:85], v[84:85], v[88:89]
	v_add3_u32 v10, v10, v105, s1
	v_bfe_u32 v88, v85, 16, 1
	v_bfe_u32 v89, v84, 16, 1
	v_add3_u32 v11, v11, v104, s1
	v_add3_u32 v84, v84, v89, s1
	v_add3_u32 v85, v85, v88, s1
	v_bfe_u32 v88, v6, 16, 1
	v_bfe_u32 v89, v7, 16, 1
	v_bfe_u32 v104, v82, 16, 1
	v_bfe_u32 v105, v83, 16, 1
	v_add3_u32 v83, v83, v105, s1
	v_add3_u32 v82, v82, v104, s1
	v_add3_u32 v7, v7, v89, s1
	v_add3_u32 v6, v6, v88, s1
	v_lshrrev_b32_e32 v6, 16, v6
	v_lshrrev_b32_e32 v7, 16, v7
	v_lshrrev_b32_e32 v82, 16, v82
	v_lshrrev_b32_e32 v83, 16, v83
	v_and_or_b32 v85, v85, s0, v83
	v_and_or_b32 v84, v84, s0, v82
	v_and_or_b32 v83, v11, s0, v7
	v_and_or_b32 v82, v10, s0, v6
	v_lshl_add_u64 v[6:7], v[148:149], 0, v[166:167]
	global_store_dwordx4 v[6:7], v[82:85], off
	v_lshlrev_b32_e32 v7, 16, v75
	v_lshlrev_b32_e32 v6, 16, v74
	v_and_b32_e32 v11, 0xffff0000, v75
	v_and_b32_e32 v10, 0xffff0000, v74
	v_pk_mul_f32 v[74:75], v[2:3], v[86:87]
	s_waitcnt vmcnt(20)
	v_lshlrev_b32_e32 v83, 16, v79
	v_lshlrev_b32_e32 v82, 16, v78
	v_pk_fma_f32 v[74:75], v[150:151], v[98:99], v[74:75]
	v_and_b32_e32 v79, 0xffff0000, v79
	v_pk_fma_f32 v[74:75], v[154:155], v[82:83], v[74:75]
	v_and_b32_e32 v78, 0xffff0000, v78
	v_pk_mul_f32 v[6:7], v[74:75], v[6:7]
	v_pk_mul_f32 v[74:75], v[20:21], v[90:91]
	v_pk_mul_f32 v[88:89], v[18:19], v[92:93]
	v_pk_fma_f32 v[74:75], v[16:17], v[94:95], v[74:75]
	v_lshlrev_b32_e32 v85, 16, v81
	v_pk_fma_f32 v[74:75], v[24:25], v[78:79], v[74:75]
	v_lshlrev_b32_e32 v84, 16, v80
	v_pk_fma_f32 v[88:89], v[14:15], v[100:101], v[88:89]
	v_pk_mul_f32 v[10:11], v[74:75], v[10:11]
	v_lshlrev_b32_e32 v75, 16, v77
	v_lshlrev_b32_e32 v74, 16, v76
	v_pk_fma_f32 v[88:89], v[22:23], v[84:85], v[88:89]
	v_and_b32_e32 v81, 0xffff0000, v81
	v_pk_mul_f32 v[74:75], v[88:89], v[74:75]
	v_pk_mul_f32 v[88:89], v[12:13], v[102:103]
	v_and_b32_e32 v80, 0xffff0000, v80
	v_pk_fma_f32 v[88:89], v[4:5], v[96:97], v[88:89]
	v_and_b32_e32 v77, 0xffff0000, v77
	v_and_b32_e32 v76, 0xffff0000, v76
	v_pk_fma_f32 v[88:89], v[8:9], v[80:81], v[88:89]
	v_bfe_u32 v94, v11, 16, 1
	v_pk_mul_f32 v[76:77], v[88:89], v[76:77]
	v_bfe_u32 v95, v10, 16, 1
	v_bfe_u32 v88, v77, 16, 1
	v_bfe_u32 v89, v76, 16, 1
	v_add3_u32 v10, v10, v95, s1
	v_add3_u32 v11, v11, v94, s1
	v_add3_u32 v76, v76, v89, s1
	v_add3_u32 v77, v77, v88, s1
	v_bfe_u32 v88, v6, 16, 1
	v_bfe_u32 v89, v7, 16, 1
	v_bfe_u32 v94, v74, 16, 1
	v_bfe_u32 v95, v75, 16, 1
	v_add3_u32 v75, v75, v95, s1
	v_add3_u32 v74, v74, v94, s1
	v_add3_u32 v7, v7, v89, s1
	v_add3_u32 v6, v6, v88, s1
	v_lshrrev_b32_e32 v6, 16, v6
	v_lshrrev_b32_e32 v7, 16, v7
	v_lshrrev_b32_e32 v74, 16, v74
	v_lshrrev_b32_e32 v75, 16, v75
	v_and_or_b32 v77, v77, s0, v75
	v_and_or_b32 v76, v76, s0, v74
	v_and_or_b32 v75, v11, s0, v7
	v_and_or_b32 v74, v10, s0, v6
	v_lshl_add_u64 v[6:7], v[148:149], 0, v[164:165]
	global_store_dwordx4 v[6:7], v[74:77], off
	v_lshlrev_b32_e32 v7, 16, v67
	v_lshlrev_b32_e32 v6, 16, v66
	v_and_b32_e32 v11, 0xffff0000, v67
	v_and_b32_e32 v10, 0xffff0000, v66
	v_pk_mul_f32 v[66:67], v[2:3], v[82:83]
	s_waitcnt vmcnt(20)
	v_lshlrev_b32_e32 v75, 16, v71
	v_lshlrev_b32_e32 v74, 16, v70
	v_pk_fma_f32 v[66:67], v[150:151], v[86:87], v[66:67]
	v_and_b32_e32 v71, 0xffff0000, v71
	v_pk_fma_f32 v[66:67], v[154:155], v[74:75], v[66:67]
	v_and_b32_e32 v70, 0xffff0000, v70
	v_pk_mul_f32 v[6:7], v[66:67], v[6:7]
	v_pk_mul_f32 v[66:67], v[20:21], v[78:79]
	v_pk_mul_f32 v[86:87], v[18:19], v[84:85]
	v_pk_fma_f32 v[66:67], v[16:17], v[90:91], v[66:67]
	v_lshlrev_b32_e32 v77, 16, v73
	v_pk_fma_f32 v[66:67], v[24:25], v[70:71], v[66:67]
	v_lshlrev_b32_e32 v76, 16, v72
	v_pk_fma_f32 v[86:87], v[14:15], v[92:93], v[86:87]
	v_pk_mul_f32 v[10:11], v[66:67], v[10:11]
	v_lshlrev_b32_e32 v67, 16, v69
	v_lshlrev_b32_e32 v66, 16, v68
	v_pk_fma_f32 v[86:87], v[22:23], v[76:77], v[86:87]
	v_and_b32_e32 v73, 0xffff0000, v73
	v_pk_mul_f32 v[66:67], v[86:87], v[66:67]
	v_pk_mul_f32 v[86:87], v[12:13], v[80:81]
	v_and_b32_e32 v72, 0xffff0000, v72
	v_pk_fma_f32 v[86:87], v[4:5], v[102:103], v[86:87]
	v_and_b32_e32 v69, 0xffff0000, v69
	v_and_b32_e32 v68, 0xffff0000, v68
	v_pk_fma_f32 v[86:87], v[8:9], v[72:73], v[86:87]
	v_bfe_u32 v88, v11, 16, 1
	v_pk_mul_f32 v[68:69], v[86:87], v[68:69]
	v_bfe_u32 v89, v10, 16, 1
	v_bfe_u32 v86, v69, 16, 1
	v_bfe_u32 v87, v68, 16, 1
	v_add3_u32 v10, v10, v89, s1
	v_add3_u32 v11, v11, v88, s1
	v_add3_u32 v68, v68, v87, s1
	v_add3_u32 v69, v69, v86, s1
	v_bfe_u32 v86, v6, 16, 1
	v_bfe_u32 v87, v7, 16, 1
	v_bfe_u32 v88, v66, 16, 1
	v_bfe_u32 v89, v67, 16, 1
	v_add3_u32 v67, v67, v89, s1
	v_add3_u32 v66, v66, v88, s1
	v_add3_u32 v7, v7, v87, s1
	v_add3_u32 v6, v6, v86, s1
	v_lshrrev_b32_e32 v6, 16, v6
	v_lshrrev_b32_e32 v7, 16, v7
	v_lshrrev_b32_e32 v66, 16, v66
	v_lshrrev_b32_e32 v67, 16, v67
	v_and_or_b32 v69, v69, s0, v67
	v_and_or_b32 v68, v68, s0, v66
	v_and_or_b32 v67, v11, s0, v7
	v_and_or_b32 v66, v10, s0, v6
	v_lshl_add_u64 v[6:7], v[148:149], 0, v[162:163]
	global_store_dwordx4 v[6:7], v[66:69], off
	s_waitcnt vmcnt(20)
	v_lshlrev_b32_e32 v7, 16, v59
	v_lshlrev_b32_e32 v6, 16, v58
	v_and_b32_e32 v11, 0xffff0000, v59
	v_and_b32_e32 v10, 0xffff0000, v58
	v_pk_mul_f32 v[58:59], v[2:3], v[74:75]
	s_waitcnt vmcnt(18)
	v_lshlrev_b32_e32 v67, 16, v63
	v_lshlrev_b32_e32 v66, 16, v62
	v_pk_fma_f32 v[58:59], v[150:151], v[82:83], v[58:59]
	v_and_b32_e32 v63, 0xffff0000, v63
	v_pk_fma_f32 v[58:59], v[154:155], v[66:67], v[58:59]
	v_and_b32_e32 v62, 0xffff0000, v62
	v_pk_mul_f32 v[6:7], v[58:59], v[6:7]
	v_pk_mul_f32 v[58:59], v[20:21], v[70:71]
	v_lshlrev_b32_e32 v69, 16, v65
	v_pk_fma_f32 v[58:59], v[16:17], v[78:79], v[58:59]
	v_pk_mul_f32 v[78:79], v[18:19], v[76:77]
	v_pk_fma_f32 v[58:59], v[24:25], v[62:63], v[58:59]
	v_lshlrev_b32_e32 v68, 16, v64
	v_pk_fma_f32 v[78:79], v[14:15], v[84:85], v[78:79]
	v_pk_mul_f32 v[10:11], v[58:59], v[10:11]
	v_lshlrev_b32_e32 v59, 16, v61
	v_lshlrev_b32_e32 v58, 16, v60
	v_pk_fma_f32 v[78:79], v[22:23], v[68:69], v[78:79]
	v_and_b32_e32 v65, 0xffff0000, v65
	v_pk_mul_f32 v[58:59], v[78:79], v[58:59]
	v_pk_mul_f32 v[78:79], v[12:13], v[72:73]
	v_and_b32_e32 v64, 0xffff0000, v64
	v_pk_fma_f32 v[78:79], v[4:5], v[80:81], v[78:79]
	v_and_b32_e32 v61, 0xffff0000, v61
	v_and_b32_e32 v60, 0xffff0000, v60
	v_pk_fma_f32 v[78:79], v[8:9], v[64:65], v[78:79]
	v_bfe_u32 v80, v11, 16, 1
	v_pk_mul_f32 v[60:61], v[78:79], v[60:61]
	v_bfe_u32 v81, v10, 16, 1
	v_bfe_u32 v78, v61, 16, 1
	v_bfe_u32 v79, v60, 16, 1
	v_add3_u32 v10, v10, v81, s1
	v_add3_u32 v11, v11, v80, s1
	v_add3_u32 v60, v60, v79, s1
	v_add3_u32 v61, v61, v78, s1
	v_bfe_u32 v78, v6, 16, 1
	v_bfe_u32 v79, v7, 16, 1
	v_bfe_u32 v80, v58, 16, 1
	v_bfe_u32 v81, v59, 16, 1
	v_add3_u32 v59, v59, v81, s1
	v_add3_u32 v58, v58, v80, s1
	v_add3_u32 v7, v7, v79, s1
	v_add3_u32 v6, v6, v78, s1
	v_lshrrev_b32_e32 v6, 16, v6
	v_lshrrev_b32_e32 v7, 16, v7
	v_lshrrev_b32_e32 v58, 16, v58
	v_lshrrev_b32_e32 v59, 16, v59
	v_and_or_b32 v61, v61, s0, v59
	v_and_or_b32 v60, v60, s0, v58
	v_and_or_b32 v59, v11, s0, v7
	v_and_or_b32 v58, v10, s0, v6
	v_lshl_add_u64 v[6:7], v[148:149], 0, v[160:161]
	global_store_dwordx4 v[6:7], v[58:61], off
	v_lshlrev_b32_e32 v7, 16, v51
	v_lshlrev_b32_e32 v6, 16, v50
	v_and_b32_e32 v11, 0xffff0000, v51
	v_and_b32_e32 v10, 0xffff0000, v50
	v_pk_mul_f32 v[50:51], v[2:3], v[66:67]
	s_waitcnt vmcnt(17)
	v_lshlrev_b32_e32 v59, 16, v55
	v_lshlrev_b32_e32 v58, 16, v54
	v_pk_fma_f32 v[50:51], v[150:151], v[74:75], v[50:51]
	v_and_b32_e32 v55, 0xffff0000, v55
	v_pk_fma_f32 v[50:51], v[154:155], v[58:59], v[50:51]
	v_and_b32_e32 v54, 0xffff0000, v54
	v_pk_mul_f32 v[6:7], v[50:51], v[6:7]
	v_pk_mul_f32 v[50:51], v[20:21], v[62:63]
	v_lshlrev_b32_e32 v61, 16, v57
	v_pk_fma_f32 v[50:51], v[16:17], v[70:71], v[50:51]
	v_pk_mul_f32 v[70:71], v[18:19], v[68:69]
	v_pk_fma_f32 v[50:51], v[24:25], v[54:55], v[50:51]
	v_lshlrev_b32_e32 v60, 16, v56
	v_pk_fma_f32 v[70:71], v[14:15], v[76:77], v[70:71]
	v_pk_mul_f32 v[10:11], v[50:51], v[10:11]
	v_lshlrev_b32_e32 v51, 16, v53
	v_lshlrev_b32_e32 v50, 16, v52
	v_pk_fma_f32 v[70:71], v[22:23], v[60:61], v[70:71]
	v_and_b32_e32 v57, 0xffff0000, v57
	v_pk_mul_f32 v[50:51], v[70:71], v[50:51]
	v_pk_mul_f32 v[70:71], v[12:13], v[64:65]
	v_and_b32_e32 v56, 0xffff0000, v56
	v_pk_fma_f32 v[70:71], v[4:5], v[72:73], v[70:71]
	v_and_b32_e32 v53, 0xffff0000, v53
	v_and_b32_e32 v52, 0xffff0000, v52
	v_pk_fma_f32 v[70:71], v[8:9], v[56:57], v[70:71]
	v_bfe_u32 v72, v11, 16, 1
	v_pk_mul_f32 v[52:53], v[70:71], v[52:53]
	v_bfe_u32 v73, v10, 16, 1
	v_bfe_u32 v70, v53, 16, 1
	v_bfe_u32 v71, v52, 16, 1
	v_add3_u32 v10, v10, v73, s1
	v_add3_u32 v11, v11, v72, s1
	v_add3_u32 v52, v52, v71, s1
	v_add3_u32 v53, v53, v70, s1
	v_bfe_u32 v70, v6, 16, 1
	v_bfe_u32 v71, v7, 16, 1
	v_bfe_u32 v72, v50, 16, 1
	v_bfe_u32 v73, v51, 16, 1
	v_add3_u32 v51, v51, v73, s1
	v_add3_u32 v50, v50, v72, s1
	v_add3_u32 v7, v7, v71, s1
	v_add3_u32 v6, v6, v70, s1
	v_lshrrev_b32_e32 v6, 16, v6
	v_lshrrev_b32_e32 v7, 16, v7
	v_lshrrev_b32_e32 v50, 16, v50
	v_lshrrev_b32_e32 v51, 16, v51
	v_and_or_b32 v53, v53, s0, v51
	v_and_or_b32 v52, v52, s0, v50
	v_and_or_b32 v51, v11, s0, v7
	v_and_or_b32 v50, v10, s0, v6
	v_lshl_add_u64 v[6:7], v[148:149], 0, v[158:159]
	global_store_dwordx4 v[6:7], v[50:53], off
	v_lshlrev_b32_e32 v7, 16, v43
	v_lshlrev_b32_e32 v6, 16, v42
	v_and_b32_e32 v11, 0xffff0000, v43
	v_and_b32_e32 v10, 0xffff0000, v42
	v_pk_mul_f32 v[42:43], v[2:3], v[58:59]
	s_waitcnt vmcnt(17)
	v_lshlrev_b32_e32 v51, 16, v47
	v_lshlrev_b32_e32 v50, 16, v46
	v_pk_fma_f32 v[42:43], v[150:151], v[66:67], v[42:43]
	v_and_b32_e32 v47, 0xffff0000, v47
	v_pk_fma_f32 v[42:43], v[154:155], v[50:51], v[42:43]
	v_and_b32_e32 v46, 0xffff0000, v46
	v_pk_mul_f32 v[6:7], v[42:43], v[6:7]
	v_pk_mul_f32 v[42:43], v[20:21], v[54:55]
	v_lshlrev_b32_e32 v53, 16, v49
	v_pk_fma_f32 v[42:43], v[16:17], v[62:63], v[42:43]
	v_pk_mul_f32 v[62:63], v[18:19], v[60:61]
	v_pk_fma_f32 v[42:43], v[24:25], v[46:47], v[42:43]
	v_lshlrev_b32_e32 v52, 16, v48
	v_pk_fma_f32 v[62:63], v[14:15], v[68:69], v[62:63]
	v_pk_mul_f32 v[10:11], v[42:43], v[10:11]
	v_lshlrev_b32_e32 v43, 16, v45
	v_lshlrev_b32_e32 v42, 16, v44
	v_pk_fma_f32 v[62:63], v[22:23], v[52:53], v[62:63]
	v_and_b32_e32 v49, 0xffff0000, v49
	v_pk_mul_f32 v[42:43], v[62:63], v[42:43]
	v_pk_mul_f32 v[62:63], v[12:13], v[56:57]
	v_and_b32_e32 v48, 0xffff0000, v48
	v_pk_fma_f32 v[62:63], v[4:5], v[64:65], v[62:63]
	v_and_b32_e32 v45, 0xffff0000, v45
	v_and_b32_e32 v44, 0xffff0000, v44
	v_pk_fma_f32 v[62:63], v[8:9], v[48:49], v[62:63]
	v_bfe_u32 v64, v11, 16, 1
	v_pk_mul_f32 v[44:45], v[62:63], v[44:45]
	v_bfe_u32 v65, v10, 16, 1
	v_bfe_u32 v62, v45, 16, 1
	v_bfe_u32 v63, v44, 16, 1
	v_add3_u32 v10, v10, v65, s1
	v_add3_u32 v11, v11, v64, s1
	v_add3_u32 v44, v44, v63, s1
	v_add3_u32 v45, v45, v62, s1
	v_bfe_u32 v62, v6, 16, 1
	v_bfe_u32 v63, v7, 16, 1
	v_bfe_u32 v64, v42, 16, 1
	v_bfe_u32 v65, v43, 16, 1
	v_add3_u32 v43, v43, v65, s1
	v_add3_u32 v42, v42, v64, s1
	v_add3_u32 v7, v7, v63, s1
	v_add3_u32 v6, v6, v62, s1
	v_lshrrev_b32_e32 v6, 16, v6
	v_lshrrev_b32_e32 v7, 16, v7
	v_lshrrev_b32_e32 v42, 16, v42
	v_lshrrev_b32_e32 v43, 16, v43
	v_and_or_b32 v45, v45, s0, v43
	v_and_or_b32 v44, v44, s0, v42
	v_and_or_b32 v43, v11, s0, v7
	v_and_or_b32 v42, v10, s0, v6
	v_lshl_add_u64 v[6:7], v[148:149], 0, v[156:157]
	global_store_dwordx4 v[6:7], v[42:45], off
	s_waitcnt vmcnt(17)
	v_lshlrev_b32_e32 v7, 16, v35
	v_lshlrev_b32_e32 v6, 16, v34
	v_and_b32_e32 v11, 0xffff0000, v35
	v_and_b32_e32 v10, 0xffff0000, v34
	v_pk_mul_f32 v[34:35], v[2:3], v[50:51]
	s_waitcnt vmcnt(15)
	v_lshlrev_b32_e32 v43, 16, v39
	v_lshlrev_b32_e32 v42, 16, v38
	v_pk_fma_f32 v[34:35], v[150:151], v[58:59], v[34:35]
	v_and_b32_e32 v39, 0xffff0000, v39
	v_pk_fma_f32 v[34:35], v[154:155], v[42:43], v[34:35]
	v_and_b32_e32 v38, 0xffff0000, v38
	v_pk_mul_f32 v[6:7], v[34:35], v[6:7]
	v_pk_mul_f32 v[34:35], v[20:21], v[46:47]
	v_lshlrev_b32_e32 v45, 16, v41
	v_pk_fma_f32 v[34:35], v[16:17], v[54:55], v[34:35]
	v_pk_mul_f32 v[54:55], v[18:19], v[52:53]
	v_pk_fma_f32 v[34:35], v[24:25], v[38:39], v[34:35]
	v_lshlrev_b32_e32 v44, 16, v40
	v_pk_fma_f32 v[54:55], v[14:15], v[60:61], v[54:55]
	v_pk_mul_f32 v[10:11], v[34:35], v[10:11]
	v_lshlrev_b32_e32 v35, 16, v37
	v_lshlrev_b32_e32 v34, 16, v36
	v_pk_fma_f32 v[54:55], v[22:23], v[44:45], v[54:55]
	v_and_b32_e32 v41, 0xffff0000, v41
	v_pk_mul_f32 v[34:35], v[54:55], v[34:35]
	v_pk_mul_f32 v[54:55], v[12:13], v[48:49]
	v_and_b32_e32 v40, 0xffff0000, v40
	v_pk_fma_f32 v[54:55], v[4:5], v[56:57], v[54:55]
	v_and_b32_e32 v37, 0xffff0000, v37
	v_and_b32_e32 v36, 0xffff0000, v36
	v_pk_fma_f32 v[54:55], v[8:9], v[40:41], v[54:55]
	v_bfe_u32 v56, v11, 16, 1
	v_pk_mul_f32 v[36:37], v[54:55], v[36:37]
	v_bfe_u32 v57, v10, 16, 1
	v_bfe_u32 v54, v37, 16, 1
	v_bfe_u32 v55, v36, 16, 1
	v_add3_u32 v10, v10, v57, s1
	v_add3_u32 v11, v11, v56, s1
	v_add3_u32 v36, v36, v55, s1
	v_add3_u32 v37, v37, v54, s1
	v_bfe_u32 v54, v6, 16, 1
	v_bfe_u32 v55, v7, 16, 1
	v_bfe_u32 v56, v34, 16, 1
	v_bfe_u32 v57, v35, 16, 1
	v_add3_u32 v35, v35, v57, s1
	v_add3_u32 v34, v34, v56, s1
	v_add3_u32 v7, v7, v55, s1
	v_add3_u32 v6, v6, v54, s1
	v_lshrrev_b32_e32 v6, 16, v6
	v_lshrrev_b32_e32 v7, 16, v7
	v_lshrrev_b32_e32 v34, 16, v34
	v_lshrrev_b32_e32 v35, 16, v35
	v_and_or_b32 v37, v37, s0, v35
	v_and_or_b32 v36, v36, s0, v34
	v_and_or_b32 v35, v11, s0, v7
	v_and_or_b32 v34, v10, s0, v6
	v_lshl_add_u64 v[6:7], v[148:149], 0, v[152:153]
	v_pk_mul_f32 v[2:3], v[2:3], v[42:43]
	global_store_dwordx4 v[6:7], v[34:37], off
	v_lshlrev_b32_e32 v7, 16, v27
	v_lshlrev_b32_e32 v6, 16, v26
	v_and_b32_e32 v11, 0xffff0000, v27
	v_and_b32_e32 v10, 0xffff0000, v26
	s_waitcnt vmcnt(15)
	v_lshlrev_b32_e32 v27, 16, v31
	v_lshlrev_b32_e32 v26, 16, v30
	v_pk_fma_f32 v[2:3], v[150:151], v[50:51], v[2:3]
	v_and_b32_e32 v31, 0xffff0000, v31
	v_pk_fma_f32 v[2:3], v[154:155], v[26:27], v[2:3]
	v_and_b32_e32 v30, 0xffff0000, v30
	v_pk_mul_f32 v[2:3], v[2:3], v[6:7]
	v_pk_mul_f32 v[6:7], v[20:21], v[38:39]
	v_pk_mul_f32 v[12:13], v[12:13], v[40:41]
	v_pk_fma_f32 v[6:7], v[16:17], v[46:47], v[6:7]
	v_pk_mul_f32 v[18:19], v[18:19], v[44:45]
	v_pk_fma_f32 v[6:7], v[24:25], v[30:31], v[6:7]
	v_and_b32_e32 v25, 0xffff0000, v33
	v_and_b32_e32 v24, 0xffff0000, v32
	v_pk_fma_f32 v[4:5], v[4:5], v[48:49], v[12:13]
	v_and_b32_e32 v17, 0xffff0000, v29
	v_and_b32_e32 v16, 0xffff0000, v28
	v_lshlrev_b32_e32 v21, 16, v33
	v_lshlrev_b32_e32 v20, 16, v32
	v_pk_fma_f32 v[14:15], v[14:15], v[52:53], v[18:19]
	v_pk_fma_f32 v[4:5], v[8:9], v[24:25], v[4:5]
	v_pk_mul_f32 v[6:7], v[6:7], v[10:11]
	v_lshlrev_b32_e32 v11, 16, v29
	v_lshlrev_b32_e32 v10, 16, v28
	v_pk_fma_f32 v[14:15], v[22:23], v[20:21], v[14:15]
	v_pk_mul_f32 v[4:5], v[4:5], v[16:17]
	v_pk_mul_f32 v[10:11], v[14:15], v[10:11]
	v_bfe_u32 v8, v5, 16, 1
	v_bfe_u32 v9, v4, 16, 1
	v_bfe_u32 v12, v7, 16, 1
	v_bfe_u32 v13, v6, 16, 1
	v_add3_u32 v6, v6, v13, s1
	v_add3_u32 v7, v7, v12, s1
	v_add3_u32 v4, v4, v9, s1
	v_add3_u32 v5, v5, v8, s1
	v_bfe_u32 v8, v2, 16, 1
	v_bfe_u32 v9, v3, 16, 1
	v_bfe_u32 v12, v10, 16, 1
	v_bfe_u32 v13, v11, 16, 1
	v_add3_u32 v11, v11, v13, s1
	v_add3_u32 v10, v10, v12, s1
	v_add3_u32 v3, v3, v9, s1
	v_add3_u32 v2, v2, v8, s1
	v_lshrrev_b32_e32 v2, 16, v2
	v_lshrrev_b32_e32 v3, 16, v3
	v_lshrrev_b32_e32 v8, 16, v10
	v_lshrrev_b32_e32 v9, 16, v11
	v_and_or_b32 v5, v5, s0, v9
	v_and_or_b32 v4, v4, s0, v8
	v_and_or_b32 v3, v7, s0, v3
	v_and_or_b32 v2, v6, s0, v2
	v_lshl_add_u64 v[6:7], v[148:149], 0, v[146:147]
	s_mov_b64 s[0:1], s[82:83]
	global_store_dwordx4 v[6:7], v[2:5], off
	s_mov_b64 s[8:9], -1
	s_nop 0
	v_mov_b32_e32 v2, v0
	s_load_dwordx2 s[6:7], s[0:1], 0x90
	s_add_i32 s0, 0, 0x21170
	v_mov_b32_e32 v2, s0
	ds_read_b32 v2, v2
	s_waitcnt lgkmcnt(0)
	s_add_u32 s0, s6, 0x1000300
	s_addc_u32 s1, s7, 0
	s_and_saveexec_b64 s[2:3], s[56:57]
	s_cbranch_execz .LBB0_162
	v_mov_b32_e32 v3, 0
	global_load_dword v3, v3, s[0:1] sc1
	s_movk_i32 s4, 0x100
	s_waitcnt vmcnt(0)
	v_cmp_gt_u32_e32 vcc, s4, v3
	s_orn2_b64 s[8:9], vcc, exec
